# group seams: L1 invalidate issued before the release poll (off the release path)
# speedup vs baseline: 1.0097x; 1.0079x over previous
; __device__ __forceinline__ unsigned xb_ld(unsigned* p)              { return __hip_atomic_load(p, __ATOMIC_RELAXED, __HIP_MEMORY_SCOPE_AGENT); }
; __device__ __forceinline__ unsigned xb_add(unsigned* p, unsigned v) { return __hip_atomic_fetch_add(p, v, __ATOMIC_RELAXED, __HIP_MEMORY_SCOPE_AGENT); }
; #define XB_SPIN(cond, bar) do { unsigned _sp = 0; while (cond) { __builtin_amdgcn_s_sleep(1); \
;     if ((++_sp & 255u) == 0u) { if (xb_ld(&(bar)[XB_TMO])) break; if (_sp > XB_SPIN_CAP) { atomicAdd(&(bar)[XB_TMO], 1u); break; } } } } while (0)
; __device__ __forceinline__ void xcd_barrier(const XcdBarrier& b) {
;     ...
;     if (threadIdx.x == 0) {
;         unsigned* bar = b.bar;
;         __builtin_amdgcn_s_waitcnt(0);
;         unsigned nloc = b.st[0], nx = b.st[1];
;         if (nloc == 0u) { xcd_barrier_complete(bar, b.x, b.gsz, nloc, nx); b.st[0] = nloc; b.st[1] = nx; }
;         const unsigned old = xb_add(&bar[XB_XSUB(b.x)], 1u);
;         const unsigned gen = old / nloc;
;         if (old + 1u == (gen + 1u) * nloc) {
;             __builtin_amdgcn_fence(__ATOMIC_RELEASE, "agent");
;             asm volatile("s_waitcnt vmcnt(0)" ::: "memory");
;             const unsigned og = xb_add(&bar[XB_TOP], 1u);
;             const unsigned tg = og / nx;
;             if (og + 1u == (tg + 1u) * nx) xb_add(&bar[XB_TOPGEN], 1u);
;             else XB_SPIN(xb_ld(&bar[XB_TOPGEN]) == tg, bar);
;             __builtin_amdgcn_fence(__ATOMIC_ACQUIRE, "agent");
;             xb_add(&bar[XB_XGEN(b.x)], 1u);
;             asm volatile("s_waitcnt vmcnt(0)" ::: "memory");
;         } else {
;             XB_SPIN(xb_ld(&bar[XB_XGEN(b.x)]) == gen, bar);
;             __builtin_amdgcn_fence(__ATOMIC_ACQUIRE, "agent");
;             asm volatile("s_waitcnt vmcnt(0)" ::: "memory");
;         }
.LBB0_199:
	s_lshl_b32 s4, s33, 8
	s_add_u32 s4, s54, s4
	s_addc_u32 s5, s55, 0
	v_mov_b32_e32 v1, 0x1000
	v_mov_b32_e32 v3, 1
	global_atomic_add v3, v1, v3, s[4:5] offset:1024 sc0
	v_cvt_f32_u32_e32 v1, v2
	v_sub_u32_e32 v4, 0, v2
	v_rcp_iflag_f32_e32 v1, v1
	s_nop 0
	v_mul_f32_e32 v1, 0x4f7ffffe, v1
	v_cvt_u32_f32_e32 v1, v1
	v_mul_lo_u32 v4, v4, v1
	v_mul_hi_u32 v4, v1, v4
	v_add_u32_e32 v1, v1, v4
	s_waitcnt vmcnt(0)
	v_mul_hi_u32 v1, v3, v1
	v_mul_lo_u32 v4, v1, v2
	v_sub_u32_e32 v4, v3, v4
	v_add_u32_e32 v5, 1, v1
	v_cmp_ge_u32_e32 vcc, v4, v2
	v_add_u32_e32 v3, 1, v3
	s_nop 0
	v_cndmask_b32_e32 v1, v1, v5, vcc
	v_sub_u32_e32 v5, v4, v2
	v_cndmask_b32_e32 v4, v4, v5, vcc
	v_add_u32_e32 v5, 1, v1
	v_cmp_ge_u32_e32 vcc, v4, v2
	s_nop 1
	v_cndmask_b32_e32 v1, v1, v5, vcc
	v_mul_lo_u32 v4, v2, v1
	v_add_u32_e32 v2, v4, v2
	v_cmp_ne_u32_e32 vcc, v3, v2
	s_and_saveexec_b64 s[20:21], vcc
	s_xor_b64 s[36:37], exec, s[20:21]
	s_cbranch_execz .LBB0_212
	s_waitcnt lgkmcnt(0)
	buffer_inv sc1
	v_mov_b32_e32 v0, 0x2000
	global_load_dword v0, v0, s[4:5] offset:1024 sc1
	s_add_u32 s40, s4, 0x2400
	s_addc_u32 s41, s5, 0
	s_waitcnt vmcnt(0)
	v_cmp_eq_u32_e32 vcc, v0, v1
	s_and_saveexec_b64 s[38:39], vcc
	s_cbranch_execz .LBB0_211
	s_mov_b32 s11, 1
	s_mov_b64 s[44:45], 0
	v_mov_b32_e32 v0, 0
	s_branch .LBB0_203

; __device__ __forceinline__ unsigned xb_ld(unsigned* p)              { return __hip_atomic_load(p, __ATOMIC_RELAXED, __HIP_MEMORY_SCOPE_AGENT); }
; #define XB_SPIN(cond, bar) do { unsigned _sp = 0; while (cond) { __builtin_amdgcn_s_sleep(1); \
;     if ((++_sp & 255u) == 0u) { if (xb_ld(&(bar)[XB_TMO])) break; if (_sp > XB_SPIN_CAP) { atomicAdd(&(bar)[XB_TMO], 1u); break; } } } } while (0)
; __device__ __forceinline__ void xcd_barrier(const XcdBarrier& b) {
;     ...
;         } else {
;             XB_SPIN(xb_ld(&bar[XB_XGEN(b.x)]) == gen, bar);
;             __builtin_amdgcn_fence(__ATOMIC_ACQUIRE, "agent");
;             asm volatile("s_waitcnt vmcnt(0)" ::: "memory");
;         }
.LBB0_211:
	s_or_b64 exec, exec, s[38:39]
	s_waitcnt vmcnt(0)
	s_waitcnt vmcnt(0)

; __device__ __forceinline__ unsigned xb_ld(unsigned* p)              { return __hip_atomic_load(p, __ATOMIC_RELAXED, __HIP_MEMORY_SCOPE_AGENT); }
; __device__ __forceinline__ unsigned xb_add(unsigned* p, unsigned v) { return __hip_atomic_fetch_add(p, v, __ATOMIC_RELAXED, __HIP_MEMORY_SCOPE_AGENT); }
; #define XB_SPIN(cond, bar) do { unsigned _sp = 0; while (cond) { __builtin_amdgcn_s_sleep(1); \
;     if ((++_sp & 255u) == 0u) { if (xb_ld(&(bar)[XB_TMO])) break; if (_sp > XB_SPIN_CAP) { atomicAdd(&(bar)[XB_TMO], 1u); break; } } } } while (0)
; __device__ __forceinline__ void xcd_barrier(const XcdBarrier& b) {
;     ...
;     if (threadIdx.x == 0) {
;         unsigned* bar = b.bar;
;         __builtin_amdgcn_s_waitcnt(0);
;         unsigned nloc = b.st[0], nx = b.st[1];
;         if (nloc == 0u) { xcd_barrier_complete(bar, b.x, b.gsz, nloc, nx); b.st[0] = nloc; b.st[1] = nx; }
;         const unsigned old = xb_add(&bar[XB_XSUB(b.x)], 1u);
;         const unsigned gen = old / nloc;
;         if (old + 1u == (gen + 1u) * nloc) {
;             __builtin_amdgcn_fence(__ATOMIC_RELEASE, "agent");
;             asm volatile("s_waitcnt vmcnt(0)" ::: "memory");
;             const unsigned og = xb_add(&bar[XB_TOP], 1u);
;             const unsigned tg = og / nx;
;             if (og + 1u == (tg + 1u) * nx) xb_add(&bar[XB_TOPGEN], 1u);
;             else XB_SPIN(xb_ld(&bar[XB_TOPGEN]) == tg, bar);
;             __builtin_amdgcn_fence(__ATOMIC_ACQUIRE, "agent");
;             xb_add(&bar[XB_XGEN(b.x)], 1u);
;             asm volatile("s_waitcnt vmcnt(0)" ::: "memory");
;         } else {
;             XB_SPIN(xb_ld(&bar[XB_XGEN(b.x)]) == gen, bar);
;             __builtin_amdgcn_fence(__ATOMIC_ACQUIRE, "agent");
;             asm volatile("s_waitcnt vmcnt(0)" ::: "memory");
;         }
.LBB0_384:
	s_lshl_b32 s4, s33, 8
	s_add_u32 s4, s54, s4
	s_addc_u32 s5, s55, 0
	v_mov_b32_e32 v1, 0x1000
	v_mov_b32_e32 v3, 1
	global_atomic_add v3, v1, v3, s[4:5] offset:1024 sc0
	v_cvt_f32_u32_e32 v1, v2
	v_sub_u32_e32 v4, 0, v2
	v_rcp_iflag_f32_e32 v1, v1
	s_nop 0
	v_mul_f32_e32 v1, 0x4f7ffffe, v1
	v_cvt_u32_f32_e32 v1, v1
	v_mul_lo_u32 v4, v4, v1
	v_mul_hi_u32 v4, v1, v4
	v_add_u32_e32 v1, v1, v4
	s_waitcnt vmcnt(0)
	v_mul_hi_u32 v1, v3, v1
	v_mul_lo_u32 v4, v1, v2
	v_sub_u32_e32 v4, v3, v4
	v_add_u32_e32 v5, 1, v1
	v_cmp_ge_u32_e32 vcc, v4, v2
	v_add_u32_e32 v3, 1, v3
	s_nop 0
	v_cndmask_b32_e32 v1, v1, v5, vcc
	v_sub_u32_e32 v5, v4, v2
	v_cndmask_b32_e32 v4, v4, v5, vcc
	v_add_u32_e32 v5, 1, v1
	v_cmp_ge_u32_e32 vcc, v4, v2
	s_nop 1
	v_cndmask_b32_e32 v1, v1, v5, vcc
	v_mul_lo_u32 v4, v2, v1
	v_add_u32_e32 v2, v4, v2
	v_cmp_ne_u32_e32 vcc, v3, v2
	s_and_saveexec_b64 s[20:21], vcc
	s_xor_b64 s[44:45], exec, s[20:21]
	s_cbranch_execz .LBB0_397
	s_waitcnt lgkmcnt(0)
	buffer_inv sc1
	v_mov_b32_e32 v0, 0x2000
	global_load_dword v0, v0, s[4:5] offset:1024 sc1
	s_add_u32 s56, s4, 0x2400
	s_addc_u32 s57, s5, 0
	s_waitcnt vmcnt(0)
	v_cmp_eq_u32_e32 vcc, v0, v1
	s_and_saveexec_b64 s[50:51], vcc
	s_cbranch_execz .LBB0_396
	s_mov_b32 s11, 1
	s_mov_b64 s[58:59], 0
	v_mov_b32_e32 v0, 0
	s_branch .LBB0_388

; __device__ __forceinline__ unsigned xb_ld(unsigned* p)              { return __hip_atomic_load(p, __ATOMIC_RELAXED, __HIP_MEMORY_SCOPE_AGENT); }
; #define XB_SPIN(cond, bar) do { unsigned _sp = 0; while (cond) { __builtin_amdgcn_s_sleep(1); \
;     if ((++_sp & 255u) == 0u) { if (xb_ld(&(bar)[XB_TMO])) break; if (_sp > XB_SPIN_CAP) { atomicAdd(&(bar)[XB_TMO], 1u); break; } } } } while (0)
; __device__ __forceinline__ void xcd_barrier(const XcdBarrier& b) {
;     ...
;         } else {
;             XB_SPIN(xb_ld(&bar[XB_XGEN(b.x)]) == gen, bar);
;             __builtin_amdgcn_fence(__ATOMIC_ACQUIRE, "agent");
;             asm volatile("s_waitcnt vmcnt(0)" ::: "memory");
;         }
.LBB0_396:
	s_or_b64 exec, exec, s[50:51]
	s_waitcnt vmcnt(0)
	s_waitcnt vmcnt(0)

; __device__ __forceinline__ unsigned xb_ld(unsigned* p)              { return __hip_atomic_load(p, __ATOMIC_RELAXED, __HIP_MEMORY_SCOPE_AGENT); }
; __device__ __forceinline__ unsigned xb_add(unsigned* p, unsigned v) { return __hip_atomic_fetch_add(p, v, __ATOMIC_RELAXED, __HIP_MEMORY_SCOPE_AGENT); }
; #define XB_SPIN(cond, bar) do { unsigned _sp = 0; while (cond) { __builtin_amdgcn_s_sleep(1); \
;     if ((++_sp & 255u) == 0u) { if (xb_ld(&(bar)[XB_TMO])) break; if (_sp > XB_SPIN_CAP) { atomicAdd(&(bar)[XB_TMO], 1u); break; } } } } while (0)
; __device__ __forceinline__ void xcd_barrier(const XcdBarrier& b) {
;     ...
;     if (threadIdx.x == 0) {
;         unsigned* bar = b.bar;
;         __builtin_amdgcn_s_waitcnt(0);
;         unsigned nloc = b.st[0], nx = b.st[1];
;         if (nloc == 0u) { xcd_barrier_complete(bar, b.x, b.gsz, nloc, nx); b.st[0] = nloc; b.st[1] = nx; }
;         const unsigned old = xb_add(&bar[XB_XSUB(b.x)], 1u);
;         const unsigned gen = old / nloc;
;         if (old + 1u == (gen + 1u) * nloc) {
;             __builtin_amdgcn_fence(__ATOMIC_RELEASE, "agent");
;             asm volatile("s_waitcnt vmcnt(0)" ::: "memory");
;             const unsigned og = xb_add(&bar[XB_TOP], 1u);
;             const unsigned tg = og / nx;
;             if (og + 1u == (tg + 1u) * nx) xb_add(&bar[XB_TOPGEN], 1u);
;             else XB_SPIN(xb_ld(&bar[XB_TOPGEN]) == tg, bar);
;             __builtin_amdgcn_fence(__ATOMIC_ACQUIRE, "agent");
;             xb_add(&bar[XB_XGEN(b.x)], 1u);
;             asm volatile("s_waitcnt vmcnt(0)" ::: "memory");
;         } else {
;             XB_SPIN(xb_ld(&bar[XB_XGEN(b.x)]) == gen, bar);
;             __builtin_amdgcn_fence(__ATOMIC_ACQUIRE, "agent");
;             asm volatile("s_waitcnt vmcnt(0)" ::: "memory");
;         }
.LBB0_439:
	s_lshl_b32 s4, s33, 8
	s_add_u32 s4, s54, s4
	s_addc_u32 s5, s55, 0
	v_mov_b32_e32 v1, 0x1000
	v_mov_b32_e32 v3, 1
	global_atomic_add v3, v1, v3, s[4:5] offset:1024 sc0
	v_cvt_f32_u32_e32 v1, v2
	v_sub_u32_e32 v4, 0, v2
	v_rcp_iflag_f32_e32 v1, v1
	s_nop 0
	v_mul_f32_e32 v1, 0x4f7ffffe, v1
	v_cvt_u32_f32_e32 v1, v1
	v_mul_lo_u32 v4, v4, v1
	v_mul_hi_u32 v4, v1, v4
	v_add_u32_e32 v1, v1, v4
	s_waitcnt vmcnt(0)
	v_mul_hi_u32 v1, v3, v1
	v_mul_lo_u32 v4, v1, v2
	v_sub_u32_e32 v4, v3, v4
	v_add_u32_e32 v5, 1, v1
	v_cmp_ge_u32_e32 vcc, v4, v2
	v_add_u32_e32 v3, 1, v3
	s_nop 0
	v_cndmask_b32_e32 v1, v1, v5, vcc
	v_sub_u32_e32 v5, v4, v2
	v_cndmask_b32_e32 v4, v4, v5, vcc
	v_add_u32_e32 v5, 1, v1
	v_cmp_ge_u32_e32 vcc, v4, v2
	s_nop 1
	v_cndmask_b32_e32 v1, v1, v5, vcc
	v_mul_lo_u32 v4, v2, v1
	v_add_u32_e32 v2, v4, v2
	v_cmp_ne_u32_e32 vcc, v3, v2
	s_and_saveexec_b64 s[20:21], vcc
	s_xor_b64 s[60:61], exec, s[20:21]
	s_cbranch_execz .LBB0_452
	s_waitcnt lgkmcnt(0)
	buffer_inv sc1
	v_mov_b32_e32 v0, 0x2000
	global_load_dword v0, v0, s[4:5] offset:1024 sc1
	s_add_u32 s64, s4, 0x2400
	s_addc_u32 s65, s5, 0
	s_waitcnt vmcnt(0)
	v_cmp_eq_u32_e32 vcc, v0, v1
	s_and_saveexec_b64 s[62:63], vcc
	s_cbranch_execz .LBB0_451
	s_mov_b32 s11, 1
	s_mov_b64 s[66:67], 0
	v_mov_b32_e32 v0, 0
	s_branch .LBB0_443

; __device__ __forceinline__ unsigned xb_ld(unsigned* p)              { return __hip_atomic_load(p, __ATOMIC_RELAXED, __HIP_MEMORY_SCOPE_AGENT); }
; #define XB_SPIN(cond, bar) do { unsigned _sp = 0; while (cond) { __builtin_amdgcn_s_sleep(1); \
;     if ((++_sp & 255u) == 0u) { if (xb_ld(&(bar)[XB_TMO])) break; if (_sp > XB_SPIN_CAP) { atomicAdd(&(bar)[XB_TMO], 1u); break; } } } } while (0)
; __device__ __forceinline__ void xcd_barrier(const XcdBarrier& b) {
;     ...
;         } else {
;             XB_SPIN(xb_ld(&bar[XB_XGEN(b.x)]) == gen, bar);
;             __builtin_amdgcn_fence(__ATOMIC_ACQUIRE, "agent");
;             asm volatile("s_waitcnt vmcnt(0)" ::: "memory");
;         }
.LBB0_451:
	s_or_b64 exec, exec, s[62:63]
	s_waitcnt vmcnt(0)
	s_waitcnt vmcnt(0)

; __device__ __forceinline__ unsigned xb_ld(unsigned* p)              { return __hip_atomic_load(p, __ATOMIC_RELAXED, __HIP_MEMORY_SCOPE_AGENT); }
; __device__ __forceinline__ unsigned xb_add(unsigned* p, unsigned v) { return __hip_atomic_fetch_add(p, v, __ATOMIC_RELAXED, __HIP_MEMORY_SCOPE_AGENT); }
; #define XB_SPIN(cond, bar) do { unsigned _sp = 0; while (cond) { __builtin_amdgcn_s_sleep(1); \
;     if ((++_sp & 255u) == 0u) { if (xb_ld(&(bar)[XB_TMO])) break; if (_sp > XB_SPIN_CAP) { atomicAdd(&(bar)[XB_TMO], 1u); break; } } } } while (0)
; __device__ __forceinline__ void xcd_barrier(const XcdBarrier& b) {
;     ...
;     if (threadIdx.x == 0) {
;         unsigned* bar = b.bar;
;         __builtin_amdgcn_s_waitcnt(0);
;         unsigned nloc = b.st[0], nx = b.st[1];
;         if (nloc == 0u) { xcd_barrier_complete(bar, b.x, b.gsz, nloc, nx); b.st[0] = nloc; b.st[1] = nx; }
;         const unsigned old = xb_add(&bar[XB_XSUB(b.x)], 1u);
;         const unsigned gen = old / nloc;
;         if (old + 1u == (gen + 1u) * nloc) {
;             __builtin_amdgcn_fence(__ATOMIC_RELEASE, "agent");
;             asm volatile("s_waitcnt vmcnt(0)" ::: "memory");
;             const unsigned og = xb_add(&bar[XB_TOP], 1u);
;             const unsigned tg = og / nx;
;             if (og + 1u == (tg + 1u) * nx) xb_add(&bar[XB_TOPGEN], 1u);
;             else XB_SPIN(xb_ld(&bar[XB_TOPGEN]) == tg, bar);
;             __builtin_amdgcn_fence(__ATOMIC_ACQUIRE, "agent");
;             xb_add(&bar[XB_XGEN(b.x)], 1u);
;             asm volatile("s_waitcnt vmcnt(0)" ::: "memory");
;         } else {
;             XB_SPIN(xb_ld(&bar[XB_XGEN(b.x)]) == gen, bar);
;             __builtin_amdgcn_fence(__ATOMIC_ACQUIRE, "agent");
;             asm volatile("s_waitcnt vmcnt(0)" ::: "memory");
;         }
.LBB0_490:
	s_lshl_b32 s2, s33, 8
	s_add_u32 s4, s54, s2
	s_addc_u32 s5, s55, 0
	v_mov_b32_e32 v1, 0x1000
	v_mov_b32_e32 v3, 1
	global_atomic_add v3, v1, v3, s[4:5] offset:1024 sc0
	v_cvt_f32_u32_e32 v1, v2
	v_sub_u32_e32 v4, 0, v2
	v_rcp_iflag_f32_e32 v1, v1
	s_nop 0
	v_mul_f32_e32 v1, 0x4f7ffffe, v1
	v_cvt_u32_f32_e32 v1, v1
	v_mul_lo_u32 v4, v4, v1
	v_mul_hi_u32 v4, v1, v4
	v_add_u32_e32 v1, v1, v4
	s_waitcnt vmcnt(0)
	v_mul_hi_u32 v1, v3, v1
	v_mul_lo_u32 v4, v1, v2
	v_sub_u32_e32 v4, v3, v4
	v_add_u32_e32 v5, 1, v1
	v_cmp_ge_u32_e32 vcc, v4, v2
	v_add_u32_e32 v3, 1, v3
	s_nop 0
	v_cndmask_b32_e32 v1, v1, v5, vcc
	v_sub_u32_e32 v5, v4, v2
	v_cndmask_b32_e32 v4, v4, v5, vcc
	v_add_u32_e32 v5, 1, v1
	v_cmp_ge_u32_e32 vcc, v4, v2
	s_nop 1
	v_cndmask_b32_e32 v1, v1, v5, vcc
	v_mul_lo_u32 v4, v2, v1
	v_add_u32_e32 v2, v4, v2
	v_cmp_ne_u32_e32 vcc, v3, v2
	s_and_saveexec_b64 s[2:3], vcc
	s_xor_b64 s[62:63], exec, s[2:3]
	s_cbranch_execz .LBB0_503
	s_waitcnt lgkmcnt(0)
	buffer_inv sc1
	v_mov_b32_e32 v0, 0x2000
	global_load_dword v0, v0, s[4:5] offset:1024 sc1
	s_add_u32 s66, s4, 0x2400
	s_addc_u32 s67, s5, 0
	s_waitcnt vmcnt(0)
	v_cmp_eq_u32_e32 vcc, v0, v1
	s_and_saveexec_b64 s[64:65], vcc
	s_cbranch_execz .LBB0_502
	s_mov_b32 s2, 1
	s_mov_b64 s[68:69], 0
	v_mov_b32_e32 v0, 0
	s_branch .LBB0_494

; __device__ __forceinline__ unsigned xb_ld(unsigned* p)              { return __hip_atomic_load(p, __ATOMIC_RELAXED, __HIP_MEMORY_SCOPE_AGENT); }
; #define XB_SPIN(cond, bar) do { unsigned _sp = 0; while (cond) { __builtin_amdgcn_s_sleep(1); \
;     if ((++_sp & 255u) == 0u) { if (xb_ld(&(bar)[XB_TMO])) break; if (_sp > XB_SPIN_CAP) { atomicAdd(&(bar)[XB_TMO], 1u); break; } } } } while (0)
; __device__ __forceinline__ void xcd_barrier(const XcdBarrier& b) {
;     ...
;         } else {
;             XB_SPIN(xb_ld(&bar[XB_XGEN(b.x)]) == gen, bar);
;             __builtin_amdgcn_fence(__ATOMIC_ACQUIRE, "agent");
;             asm volatile("s_waitcnt vmcnt(0)" ::: "memory");
;         }
.LBB0_502:
	s_or_b64 exec, exec, s[64:65]
	s_waitcnt vmcnt(0)
	s_waitcnt vmcnt(0)

; __device__ __forceinline__ unsigned xb_ld(unsigned* p)              { return __hip_atomic_load(p, __ATOMIC_RELAXED, __HIP_MEMORY_SCOPE_AGENT); }
; __device__ __forceinline__ unsigned xb_add(unsigned* p, unsigned v) { return __hip_atomic_fetch_add(p, v, __ATOMIC_RELAXED, __HIP_MEMORY_SCOPE_AGENT); }
; #define XB_SPIN(cond, bar) do { unsigned _sp = 0; while (cond) { __builtin_amdgcn_s_sleep(1); \
;     if ((++_sp & 255u) == 0u) { if (xb_ld(&(bar)[XB_TMO])) break; if (_sp > XB_SPIN_CAP) { atomicAdd(&(bar)[XB_TMO], 1u); break; } } } } while (0)
; __device__ __forceinline__ void xcd_barrier(const XcdBarrier& b) {
;     ...
;     if (threadIdx.x == 0) {
;         unsigned* bar = b.bar;
;         __builtin_amdgcn_s_waitcnt(0);
;         unsigned nloc = b.st[0], nx = b.st[1];
;         if (nloc == 0u) { xcd_barrier_complete(bar, b.x, b.gsz, nloc, nx); b.st[0] = nloc; b.st[1] = nx; }
;         const unsigned old = xb_add(&bar[XB_XSUB(b.x)], 1u);
;         const unsigned gen = old / nloc;
;         if (old + 1u == (gen + 1u) * nloc) {
;             __builtin_amdgcn_fence(__ATOMIC_RELEASE, "agent");
;             asm volatile("s_waitcnt vmcnt(0)" ::: "memory");
;             const unsigned og = xb_add(&bar[XB_TOP], 1u);
;             const unsigned tg = og / nx;
;             if (og + 1u == (tg + 1u) * nx) xb_add(&bar[XB_TOPGEN], 1u);
;             else XB_SPIN(xb_ld(&bar[XB_TOPGEN]) == tg, bar);
;             __builtin_amdgcn_fence(__ATOMIC_ACQUIRE, "agent");
;             xb_add(&bar[XB_XGEN(b.x)], 1u);
;             asm volatile("s_waitcnt vmcnt(0)" ::: "memory");
;         } else {
;             XB_SPIN(xb_ld(&bar[XB_XGEN(b.x)]) == gen, bar);
;             __builtin_amdgcn_fence(__ATOMIC_ACQUIRE, "agent");
;             asm volatile("s_waitcnt vmcnt(0)" ::: "memory");
;         }
.LBB0_540:
	s_lshl_b32 s2, s33, 8
	s_add_u32 s6, s54, s2
	s_addc_u32 s7, s55, 0
	v_mov_b32_e32 v1, 0x1000
	v_mov_b32_e32 v3, 1
	global_atomic_add v3, v1, v3, s[6:7] offset:1024 sc0
	v_cvt_f32_u32_e32 v1, v2
	v_sub_u32_e32 v4, 0, v2
	v_rcp_iflag_f32_e32 v1, v1
	s_nop 0
	v_mul_f32_e32 v1, 0x4f7ffffe, v1
	v_cvt_u32_f32_e32 v1, v1
	v_mul_lo_u32 v4, v4, v1
	v_mul_hi_u32 v4, v1, v4
	v_add_u32_e32 v1, v1, v4
	s_waitcnt vmcnt(0)
	v_mul_hi_u32 v1, v3, v1
	v_mul_lo_u32 v4, v1, v2
	v_sub_u32_e32 v4, v3, v4
	v_add_u32_e32 v5, 1, v1
	v_cmp_ge_u32_e32 vcc, v4, v2
	v_add_u32_e32 v3, 1, v3
	s_nop 0
	v_cndmask_b32_e32 v1, v1, v5, vcc
	v_sub_u32_e32 v5, v4, v2
	v_cndmask_b32_e32 v4, v4, v5, vcc
	v_add_u32_e32 v5, 1, v1
	v_cmp_ge_u32_e32 vcc, v4, v2
	s_nop 1
	v_cndmask_b32_e32 v1, v1, v5, vcc
	v_mul_lo_u32 v4, v2, v1
	v_add_u32_e32 v2, v4, v2
	v_cmp_ne_u32_e32 vcc, v3, v2
	s_and_saveexec_b64 s[2:3], vcc
	s_xor_b64 s[64:65], exec, s[2:3]
	s_cbranch_execz .LBB0_553
	s_waitcnt lgkmcnt(0)
	buffer_inv sc1
	v_mov_b32_e32 v0, 0x2000
	global_load_dword v0, v0, s[6:7] offset:1024 sc1
	s_add_u32 s68, s6, 0x2400
	s_addc_u32 s69, s7, 0
	s_waitcnt vmcnt(0)
	v_cmp_eq_u32_e32 vcc, v0, v1
	s_and_saveexec_b64 s[66:67], vcc
	s_cbranch_execz .LBB0_552
	s_mov_b32 s2, 1
	s_mov_b64 s[70:71], 0
	v_mov_b32_e32 v0, 0
	s_branch .LBB0_544

; __device__ __forceinline__ unsigned xb_ld(unsigned* p)              { return __hip_atomic_load(p, __ATOMIC_RELAXED, __HIP_MEMORY_SCOPE_AGENT); }
; #define XB_SPIN(cond, bar) do { unsigned _sp = 0; while (cond) { __builtin_amdgcn_s_sleep(1); \
;     if ((++_sp & 255u) == 0u) { if (xb_ld(&(bar)[XB_TMO])) break; if (_sp > XB_SPIN_CAP) { atomicAdd(&(bar)[XB_TMO], 1u); break; } } } } while (0)
; __device__ __forceinline__ void xcd_barrier(const XcdBarrier& b) {
;     ...
;         } else {
;             XB_SPIN(xb_ld(&bar[XB_XGEN(b.x)]) == gen, bar);
;             __builtin_amdgcn_fence(__ATOMIC_ACQUIRE, "agent");
;             asm volatile("s_waitcnt vmcnt(0)" ::: "memory");
;         }
.LBB0_552:
	s_or_b64 exec, exec, s[66:67]
	s_waitcnt vmcnt(0)
	s_waitcnt vmcnt(0)

; __device__ __forceinline__ unsigned xb_ld(unsigned* p)              { return __hip_atomic_load(p, __ATOMIC_RELAXED, __HIP_MEMORY_SCOPE_AGENT); }
; __device__ __forceinline__ unsigned xb_add(unsigned* p, unsigned v) { return __hip_atomic_fetch_add(p, v, __ATOMIC_RELAXED, __HIP_MEMORY_SCOPE_AGENT); }
; #define XB_SPIN(cond, bar) do { unsigned _sp = 0; while (cond) { __builtin_amdgcn_s_sleep(1); \
;     if ((++_sp & 255u) == 0u) { if (xb_ld(&(bar)[XB_TMO])) break; if (_sp > XB_SPIN_CAP) { atomicAdd(&(bar)[XB_TMO], 1u); break; } } } } while (0)
; __device__ __forceinline__ void xcd_barrier(const XcdBarrier& b) {
;     ...
;     if (threadIdx.x == 0) {
;         unsigned* bar = b.bar;
;         __builtin_amdgcn_s_waitcnt(0);
;         unsigned nloc = b.st[0], nx = b.st[1];
;         if (nloc == 0u) { xcd_barrier_complete(bar, b.x, b.gsz, nloc, nx); b.st[0] = nloc; b.st[1] = nx; }
;         const unsigned old = xb_add(&bar[XB_XSUB(b.x)], 1u);
;         const unsigned gen = old / nloc;
;         if (old + 1u == (gen + 1u) * nloc) {
;             __builtin_amdgcn_fence(__ATOMIC_RELEASE, "agent");
;             asm volatile("s_waitcnt vmcnt(0)" ::: "memory");
;             const unsigned og = xb_add(&bar[XB_TOP], 1u);
;             const unsigned tg = og / nx;
;             if (og + 1u == (tg + 1u) * nx) xb_add(&bar[XB_TOPGEN], 1u);
;             else XB_SPIN(xb_ld(&bar[XB_TOPGEN]) == tg, bar);
;             __builtin_amdgcn_fence(__ATOMIC_ACQUIRE, "agent");
;             xb_add(&bar[XB_XGEN(b.x)], 1u);
;             asm volatile("s_waitcnt vmcnt(0)" ::: "memory");
;         } else {
;             XB_SPIN(xb_ld(&bar[XB_XGEN(b.x)]) == gen, bar);
;             __builtin_amdgcn_fence(__ATOMIC_ACQUIRE, "agent");
;             asm volatile("s_waitcnt vmcnt(0)" ::: "memory");
;         }
.LBB0_1072:
	s_lshl_b32 s2, s33, 8
	s_add_u32 s6, s54, s2
	s_addc_u32 s7, s55, 0
	v_mov_b32_e32 v1, 0x1000
	v_mov_b32_e32 v3, 1
	global_atomic_add v3, v1, v3, s[6:7] offset:1024 sc0
	v_cvt_f32_u32_e32 v1, v2
	v_sub_u32_e32 v4, 0, v2
	v_rcp_iflag_f32_e32 v1, v1
	s_nop 0
	v_mul_f32_e32 v1, 0x4f7ffffe, v1
	v_cvt_u32_f32_e32 v1, v1
	v_mul_lo_u32 v4, v4, v1
	v_mul_hi_u32 v4, v1, v4
	v_add_u32_e32 v1, v1, v4
	s_waitcnt vmcnt(0)
	v_mul_hi_u32 v1, v3, v1
	v_mul_lo_u32 v4, v1, v2
	v_sub_u32_e32 v4, v3, v4
	v_add_u32_e32 v5, 1, v1
	v_cmp_ge_u32_e32 vcc, v4, v2
	v_add_u32_e32 v3, 1, v3
	s_nop 0
	v_cndmask_b32_e32 v1, v1, v5, vcc
	v_sub_u32_e32 v5, v4, v2
	v_cndmask_b32_e32 v4, v4, v5, vcc
	v_add_u32_e32 v5, 1, v1
	v_cmp_ge_u32_e32 vcc, v4, v2
	s_nop 1
	v_cndmask_b32_e32 v1, v1, v5, vcc
	v_mul_lo_u32 v4, v2, v1
	v_add_u32_e32 v2, v4, v2
	v_cmp_ne_u32_e32 vcc, v3, v2
	s_and_saveexec_b64 s[2:3], vcc
	s_xor_b64 s[12:13], exec, s[2:3]
	s_cbranch_execz .LBB0_1085
	s_waitcnt lgkmcnt(0)
	buffer_inv sc1
	v_mov_b32_e32 v0, 0x2000
	global_load_dword v0, v0, s[6:7] offset:1024 sc1
	s_add_u32 s16, s6, 0x2400
	s_addc_u32 s17, s7, 0
	s_waitcnt vmcnt(0)
	v_cmp_eq_u32_e32 vcc, v0, v1
	s_and_saveexec_b64 s[14:15], vcc
	s_cbranch_execz .LBB0_1084
	s_mov_b32 s2, 1
	s_mov_b64 s[46:47], 0
	v_mov_b32_e32 v0, 0
	s_branch .LBB0_1076

; __device__ __forceinline__ unsigned xb_ld(unsigned* p)              { return __hip_atomic_load(p, __ATOMIC_RELAXED, __HIP_MEMORY_SCOPE_AGENT); }
; #define XB_SPIN(cond, bar) do { unsigned _sp = 0; while (cond) { __builtin_amdgcn_s_sleep(1); \
;     if ((++_sp & 255u) == 0u) { if (xb_ld(&(bar)[XB_TMO])) break; if (_sp > XB_SPIN_CAP) { atomicAdd(&(bar)[XB_TMO], 1u); break; } } } } while (0)
; __device__ __forceinline__ void xcd_barrier(const XcdBarrier& b) {
;     ...
;         } else {
;             XB_SPIN(xb_ld(&bar[XB_XGEN(b.x)]) == gen, bar);
;             __builtin_amdgcn_fence(__ATOMIC_ACQUIRE, "agent");
;             asm volatile("s_waitcnt vmcnt(0)" ::: "memory");
;         }
.LBB0_1084:
	s_or_b64 exec, exec, s[14:15]
	s_waitcnt vmcnt(0)
	s_waitcnt vmcnt(0)

; __device__ __forceinline__ unsigned xb_ld(unsigned* p)              { return __hip_atomic_load(p, __ATOMIC_RELAXED, __HIP_MEMORY_SCOPE_AGENT); }
; __device__ __forceinline__ unsigned xb_add(unsigned* p, unsigned v) { return __hip_atomic_fetch_add(p, v, __ATOMIC_RELAXED, __HIP_MEMORY_SCOPE_AGENT); }
; #define XB_SPIN(cond, bar) do { unsigned _sp = 0; while (cond) { __builtin_amdgcn_s_sleep(1); \
;     if ((++_sp & 255u) == 0u) { if (xb_ld(&(bar)[XB_TMO])) break; if (_sp > XB_SPIN_CAP) { atomicAdd(&(bar)[XB_TMO], 1u); break; } } } } while (0)
; __device__ __forceinline__ void xcd_barrier(const XcdBarrier& b) {
;     ...
;     if (threadIdx.x == 0) {
;         unsigned* bar = b.bar;
;         __builtin_amdgcn_s_waitcnt(0);
;         unsigned nloc = b.st[0], nx = b.st[1];
;         if (nloc == 0u) { xcd_barrier_complete(bar, b.x, b.gsz, nloc, nx); b.st[0] = nloc; b.st[1] = nx; }
;         const unsigned old = xb_add(&bar[XB_XSUB(b.x)], 1u);
;         const unsigned gen = old / nloc;
;         if (old + 1u == (gen + 1u) * nloc) {
;             __builtin_amdgcn_fence(__ATOMIC_RELEASE, "agent");
;             asm volatile("s_waitcnt vmcnt(0)" ::: "memory");
;             const unsigned og = xb_add(&bar[XB_TOP], 1u);
;             const unsigned tg = og / nx;
;             if (og + 1u == (tg + 1u) * nx) xb_add(&bar[XB_TOPGEN], 1u);
;             else XB_SPIN(xb_ld(&bar[XB_TOPGEN]) == tg, bar);
;             __builtin_amdgcn_fence(__ATOMIC_ACQUIRE, "agent");
;             xb_add(&bar[XB_XGEN(b.x)], 1u);
;             asm volatile("s_waitcnt vmcnt(0)" ::: "memory");
;         } else {
;             XB_SPIN(xb_ld(&bar[XB_XGEN(b.x)]) == gen, bar);
;             __builtin_amdgcn_fence(__ATOMIC_ACQUIRE, "agent");
;             asm volatile("s_waitcnt vmcnt(0)" ::: "memory");
;         }
.LBB0_1123:
	s_lshl_b32 s4, s33, 8
	s_add_u32 s4, s54, s4
	s_addc_u32 s5, s55, 0
	v_mov_b32_e32 v1, 0x1000
	v_mov_b32_e32 v3, 1
	global_atomic_add v3, v1, v3, s[4:5] offset:1024 sc0
	v_cvt_f32_u32_e32 v1, v2
	v_sub_u32_e32 v4, 0, v2
	v_rcp_iflag_f32_e32 v1, v1
	s_nop 0
	v_mul_f32_e32 v1, 0x4f7ffffe, v1
	v_cvt_u32_f32_e32 v1, v1
	v_mul_lo_u32 v4, v4, v1
	v_mul_hi_u32 v4, v1, v4
	v_add_u32_e32 v1, v1, v4
	s_waitcnt vmcnt(0)
	v_mul_hi_u32 v1, v3, v1
	v_mul_lo_u32 v4, v1, v2
	v_sub_u32_e32 v4, v3, v4
	v_add_u32_e32 v5, 1, v1
	v_cmp_ge_u32_e32 vcc, v4, v2
	v_add_u32_e32 v3, 1, v3
	s_nop 0
	v_cndmask_b32_e32 v1, v1, v5, vcc
	v_sub_u32_e32 v5, v4, v2
	v_cndmask_b32_e32 v4, v4, v5, vcc
	v_add_u32_e32 v5, 1, v1
	v_cmp_ge_u32_e32 vcc, v4, v2
	s_nop 1
	v_cndmask_b32_e32 v1, v1, v5, vcc
	v_mul_lo_u32 v4, v2, v1
	v_add_u32_e32 v2, v4, v2
	v_cmp_ne_u32_e32 vcc, v3, v2
	s_and_saveexec_b64 s[6:7], vcc
	s_xor_b64 s[6:7], exec, s[6:7]
	s_cbranch_execz .LBB0_1136
	s_waitcnt lgkmcnt(0)
	buffer_inv sc1
	v_mov_b32_e32 v0, 0x2000
	global_load_dword v0, v0, s[4:5] offset:1024 sc1
	s_add_u32 s14, s4, 0x2400
	s_addc_u32 s15, s5, 0
	s_waitcnt vmcnt(0)
	v_cmp_eq_u32_e32 vcc, v0, v1
	s_and_saveexec_b64 s[12:13], vcc
	s_cbranch_execz .LBB0_1135
	s_mov_b32 s11, 1
	s_mov_b64 s[16:17], 0
	v_mov_b32_e32 v0, 0
	s_branch .LBB0_1127

; __device__ __forceinline__ unsigned xb_ld(unsigned* p)              { return __hip_atomic_load(p, __ATOMIC_RELAXED, __HIP_MEMORY_SCOPE_AGENT); }
; #define XB_SPIN(cond, bar) do { unsigned _sp = 0; while (cond) { __builtin_amdgcn_s_sleep(1); \
;     if ((++_sp & 255u) == 0u) { if (xb_ld(&(bar)[XB_TMO])) break; if (_sp > XB_SPIN_CAP) { atomicAdd(&(bar)[XB_TMO], 1u); break; } } } } while (0)
; __device__ __forceinline__ void xcd_barrier(const XcdBarrier& b) {
;     ...
;         } else {
;             XB_SPIN(xb_ld(&bar[XB_XGEN(b.x)]) == gen, bar);
;             __builtin_amdgcn_fence(__ATOMIC_ACQUIRE, "agent");
;             asm volatile("s_waitcnt vmcnt(0)" ::: "memory");
;         }
.LBB0_1135:
	s_or_b64 exec, exec, s[12:13]
	s_waitcnt vmcnt(0)
	s_waitcnt vmcnt(0)

; __device__ __forceinline__ unsigned xb_ld(unsigned* p)              { return __hip_atomic_load(p, __ATOMIC_RELAXED, __HIP_MEMORY_SCOPE_AGENT); }
; __device__ __forceinline__ unsigned xb_add(unsigned* p, unsigned v) { return __hip_atomic_fetch_add(p, v, __ATOMIC_RELAXED, __HIP_MEMORY_SCOPE_AGENT); }
; #define XB_SPIN(cond, bar) do { unsigned _sp = 0; while (cond) { __builtin_amdgcn_s_sleep(1); \
;     if ((++_sp & 255u) == 0u) { if (xb_ld(&(bar)[XB_TMO])) break; if (_sp > XB_SPIN_CAP) { atomicAdd(&(bar)[XB_TMO], 1u); break; } } } } while (0)
; __device__ __forceinline__ void xcd_barrier(const XcdBarrier& b) {
;     ...
;     if (threadIdx.x == 0) {
;         unsigned* bar = b.bar;
;         __builtin_amdgcn_s_waitcnt(0);
;         unsigned nloc = b.st[0], nx = b.st[1];
;         if (nloc == 0u) { xcd_barrier_complete(bar, b.x, b.gsz, nloc, nx); b.st[0] = nloc; b.st[1] = nx; }
;         const unsigned old = xb_add(&bar[XB_XSUB(b.x)], 1u);
;         const unsigned gen = old / nloc;
;         if (old + 1u == (gen + 1u) * nloc) {
;             __builtin_amdgcn_fence(__ATOMIC_RELEASE, "agent");
;             asm volatile("s_waitcnt vmcnt(0)" ::: "memory");
;             const unsigned og = xb_add(&bar[XB_TOP], 1u);
;             const unsigned tg = og / nx;
;             if (og + 1u == (tg + 1u) * nx) xb_add(&bar[XB_TOPGEN], 1u);
;             else XB_SPIN(xb_ld(&bar[XB_TOPGEN]) == tg, bar);
;             __builtin_amdgcn_fence(__ATOMIC_ACQUIRE, "agent");
;             xb_add(&bar[XB_XGEN(b.x)], 1u);
;             asm volatile("s_waitcnt vmcnt(0)" ::: "memory");
;         } else {
;             XB_SPIN(xb_ld(&bar[XB_XGEN(b.x)]) == gen, bar);
;             __builtin_amdgcn_fence(__ATOMIC_ACQUIRE, "agent");
;             asm volatile("s_waitcnt vmcnt(0)" ::: "memory");
;         }
.LBB0_1401:
	s_lshl_b32 s4, s33, 8
	s_add_u32 s4, s54, s4
	s_addc_u32 s5, s55, 0
	v_mov_b32_e32 v1, 0x1000
	v_mov_b32_e32 v3, 1
	global_atomic_add v3, v1, v3, s[4:5] offset:1024 sc0
	v_cvt_f32_u32_e32 v1, v2
	v_sub_u32_e32 v4, 0, v2
	v_rcp_iflag_f32_e32 v1, v1
	s_nop 0
	v_mul_f32_e32 v1, 0x4f7ffffe, v1
	v_cvt_u32_f32_e32 v1, v1
	v_mul_lo_u32 v4, v4, v1
	v_mul_hi_u32 v4, v1, v4
	v_add_u32_e32 v1, v1, v4
	s_waitcnt vmcnt(0)
	v_mul_hi_u32 v1, v3, v1
	v_mul_lo_u32 v4, v1, v2
	v_sub_u32_e32 v4, v3, v4
	v_add_u32_e32 v5, 1, v1
	v_cmp_ge_u32_e32 vcc, v4, v2
	v_add_u32_e32 v3, 1, v3
	s_nop 0
	v_cndmask_b32_e32 v1, v1, v5, vcc
	v_sub_u32_e32 v5, v4, v2
	v_cndmask_b32_e32 v4, v4, v5, vcc
	v_add_u32_e32 v5, 1, v1
	v_cmp_ge_u32_e32 vcc, v4, v2
	s_nop 1
	v_cndmask_b32_e32 v1, v1, v5, vcc
	v_mul_lo_u32 v4, v2, v1
	v_add_u32_e32 v2, v4, v2
	v_cmp_ne_u32_e32 vcc, v3, v2
	s_and_saveexec_b64 s[6:7], vcc
	s_xor_b64 s[6:7], exec, s[6:7]
	s_cbranch_execz .LBB0_1414
	s_waitcnt lgkmcnt(0)
	buffer_inv sc1
	v_mov_b32_e32 v0, 0x2000
	global_load_dword v0, v0, s[4:5] offset:1024 sc1
	s_add_u32 s10, s4, 0x2400
	s_addc_u32 s11, s5, 0
	s_waitcnt vmcnt(0)
	v_cmp_eq_u32_e32 vcc, v0, v1
	s_and_saveexec_b64 s[8:9], vcc
	s_cbranch_execz .LBB0_1413
	s_mov_b32 s20, 1
	s_mov_b64 s[12:13], 0
	v_mov_b32_e32 v0, 0
	s_branch .LBB0_1405

; __device__ __forceinline__ unsigned xb_ld(unsigned* p)              { return __hip_atomic_load(p, __ATOMIC_RELAXED, __HIP_MEMORY_SCOPE_AGENT); }
; #define XB_SPIN(cond, bar) do { unsigned _sp = 0; while (cond) { __builtin_amdgcn_s_sleep(1); \
;     if ((++_sp & 255u) == 0u) { if (xb_ld(&(bar)[XB_TMO])) break; if (_sp > XB_SPIN_CAP) { atomicAdd(&(bar)[XB_TMO], 1u); break; } } } } while (0)
; __device__ __forceinline__ void xcd_barrier(const XcdBarrier& b) {
;     ...
;         } else {
;             XB_SPIN(xb_ld(&bar[XB_XGEN(b.x)]) == gen, bar);
;             __builtin_amdgcn_fence(__ATOMIC_ACQUIRE, "agent");
;             asm volatile("s_waitcnt vmcnt(0)" ::: "memory");
;         }
.LBB0_1413:
	s_or_b64 exec, exec, s[8:9]
	s_waitcnt vmcnt(0)
	s_waitcnt vmcnt(0)
